# grid-barrier spin loops without the s_sleep back-off
# baseline (speedup 1.0000x reference)
.LBB0_80:
	global_load_dword v2, v0, s[4:5] offset:32 sc1
	s_waitcnt vmcnt(0)
	v_and_b32_e32 v2, 0xffff0000, v2
	v_cmp_ne_u32_e32 vcc, v2, v1
	s_or_b64 s[6:7], vcc, s[6:7]
	s_andn2_b64 exec, exec, s[6:7]
	s_cbranch_execnz .LBB0_80

.LBB0_96:
	flat_load_dword v51, v[4:5] sc1
	flat_load_dword v36, v[6:7] sc1
	flat_load_dword v37, v[8:9] sc1
	flat_load_dword v38, v[10:11] sc1
	flat_load_dword v39, v[12:13] sc1
	flat_load_dword v40, v[14:15] sc1
	flat_load_dword v41, v[16:17] sc1
	flat_load_dword v42, v[18:19] sc1
	flat_load_dword v43, v[20:21] sc1
	flat_load_dword v44, v[22:23] sc1
	flat_load_dword v45, v[24:25] sc1
	flat_load_dword v46, v[26:27] sc1
	flat_load_dword v47, v[28:29] sc1
	flat_load_dword v48, v[30:31] sc1
	flat_load_dword v49, v[32:33] sc1
	flat_load_dword v50, v[34:35] sc1
	s_or_b64 s[8:9], s[8:9], exec
	s_or_b64 s[6:7], s[6:7], exec
	s_waitcnt vmcnt(0) lgkmcnt(0)
	v_add_u32_e32 v52, v36, v51
	v_add_u32_e32 v52, v52, v37
	v_add_u32_e32 v52, v52, v38
	v_add_u32_e32 v52, v52, v39
	v_add_u32_e32 v52, v52, v40
	v_add_u32_e32 v52, v52, v41
	v_add_u32_e32 v52, v52, v42
	v_add_u32_e32 v52, v52, v43
	v_add_u32_e32 v52, v52, v44
	v_add_u32_e32 v52, v52, v45
	v_add_u32_e32 v52, v52, v46
	v_add_u32_e32 v52, v52, v47
	v_add_u32_e32 v52, v52, v48
	v_add_u32_e32 v52, v52, v49
	v_add_u32_e32 v52, v52, v50
	v_cmp_ne_u32_e32 vcc, s20, v52
	s_and_saveexec_b64 s[10:11], vcc
	s_cbranch_execz .LBB0_95
	s_and_b32 s14, s21, 0xff
	s_mov_b64 s[12:13], -1
	s_cmp_eq_u32 s14, 0
	s_mov_b64 s[16:17], -1
	s_mov_b64 s[14:15], -1
	s_cbranch_scc1 .LBB0_99
	s_and_saveexec_b64 s[18:19], s[16:17]
	s_cbranch_execz .LBB0_94
	s_branch .LBB0_102

.LBB0_110:
	s_and_b32 s14, s20, 0xff
	s_mov_b64 s[12:13], -1
	s_cmp_lg_u32 s14, 0
	s_mov_b64 s[14:15], -1
	s_cbranch_scc1 .LBB0_114
	flat_load_dword v4, v[0:1] sc1
	s_mov_b64 s[14:15], 0
	s_mov_b64 s[16:17], -1
	s_waitcnt vmcnt(0) lgkmcnt(0)
	v_cmp_eq_u32_e32 vcc, 0, v4
	s_and_saveexec_b64 s[18:19], vcc
	s_cmp_lt_u32 s20, 0x40001
	s_cselect_b64 s[14:15], -1, 0
	s_xor_b64 s[16:17], exec, -1
	s_and_b64 s[14:15], s[14:15], exec
	s_or_b64 exec, exec, s[18:19]

.LBB0_124:
	s_and_b32 s10, s18, 0xff
	s_cmp_lg_u32 s10, 0
	s_mov_b64 s[12:13], -1
	s_cbranch_scc0 .LBB0_126
	s_mov_b64 s[14:15], -1
	s_and_saveexec_b64 s[16:17], s[12:13]
	s_cbranch_execz .LBB0_123
	s_branch .LBB0_129

.LBB0_853:
	flat_load_dword v51, v[4:5] sc1
	flat_load_dword v36, v[6:7] sc1
	flat_load_dword v37, v[8:9] sc1
	flat_load_dword v38, v[10:11] sc1
	flat_load_dword v39, v[12:13] sc1
	flat_load_dword v40, v[14:15] sc1
	flat_load_dword v41, v[16:17] sc1
	flat_load_dword v42, v[18:19] sc1
	flat_load_dword v43, v[20:21] sc1
	flat_load_dword v44, v[22:23] sc1
	flat_load_dword v45, v[24:25] sc1
	flat_load_dword v46, v[26:27] sc1
	flat_load_dword v47, v[28:29] sc1
	flat_load_dword v48, v[30:31] sc1
	flat_load_dword v49, v[32:33] sc1
	flat_load_dword v50, v[34:35] sc1
	s_or_b64 s[10:11], s[10:11], exec
	s_or_b64 s[8:9], s[8:9], exec
	s_waitcnt vmcnt(0) lgkmcnt(0)
	v_add_u32_e32 v52, v36, v51
	v_add_u32_e32 v52, v52, v37
	v_add_u32_e32 v52, v52, v38
	v_add_u32_e32 v52, v52, v39
	v_add_u32_e32 v52, v52, v40
	v_add_u32_e32 v52, v52, v41
	v_add_u32_e32 v52, v52, v42
	v_add_u32_e32 v52, v52, v43
	v_add_u32_e32 v52, v52, v44
	v_add_u32_e32 v52, v52, v45
	v_add_u32_e32 v52, v52, v46
	v_add_u32_e32 v52, v52, v47
	v_add_u32_e32 v52, v52, v48
	v_add_u32_e32 v52, v52, v49
	v_add_u32_e32 v52, v52, v50
	v_cmp_ne_u32_e32 vcc, s22, v52
	s_and_saveexec_b64 s[12:13], vcc
	s_cbranch_execz .LBB0_852
	s_and_b32 s16, s23, 0xff
	s_mov_b64 s[14:15], -1
	s_cmp_eq_u32 s16, 0
	s_mov_b64 s[18:19], -1
	s_mov_b64 s[16:17], -1
	s_cbranch_scc1 .LBB0_856
	s_and_saveexec_b64 s[20:21], s[18:19]
	s_cbranch_execz .LBB0_851
	s_branch .LBB0_859

.LBB0_867:
	s_and_b32 s16, s22, 0xff
	s_mov_b64 s[14:15], -1
	s_cmp_lg_u32 s16, 0
	s_mov_b64 s[16:17], -1
	s_cbranch_scc1 .LBB0_871
	flat_load_dword v4, v[0:1] sc1
	s_mov_b64 s[16:17], 0
	s_mov_b64 s[18:19], -1
	s_waitcnt vmcnt(0) lgkmcnt(0)
	v_cmp_eq_u32_e32 vcc, 0, v4
	s_and_saveexec_b64 s[20:21], vcc
	s_cmp_lt_u32 s22, 0x40001
	s_cselect_b64 s[16:17], -1, 0
	s_xor_b64 s[18:19], exec, -1
	s_and_b64 s[16:17], s[16:17], exec
	s_or_b64 exec, exec, s[20:21]

.LBB0_881:
	s_and_b32 s12, s20, 0xff
	s_cmp_lg_u32 s12, 0
	s_mov_b64 s[14:15], -1
	s_cbranch_scc0 .LBB0_883
	s_mov_b64 s[16:17], -1
	s_and_saveexec_b64 s[18:19], s[14:15]
	s_cbranch_execz .LBB0_880
	s_branch .LBB0_886
